# same NA parity specialization, with dead-space padding after the NA loops so every later loop keeps its byte phase modulo 4 KiB
# speedup vs baseline: 1.0068x; 1.0068x over previous
; template <int KIND> ...
;     ...
;             if (t + 1 < nt) ATT_STORE((t + 1) & 1);
;             __syncthreads();
;         }
nap1_164:
	s_cmp_eq_u32 s95, s81
	v_add_u32_e32 v237, 0x7c, v237
	s_waitcnt lgkmcnt(0)
	s_barrier
	s_cbranch_scc1 .LBB0_125
	s_mov_b32 s83, s81
	s_branch nap1_145
	s_nop 0
	s_nop 0
	s_nop 0
	s_nop 0
	s_nop 0
	s_nop 0
	s_nop 0
	s_nop 0
	s_nop 0
	s_nop 0
	s_nop 0
	s_nop 0
	s_nop 0
	s_nop 0
	s_nop 0
	s_nop 0
	s_nop 0
	s_nop 0
	s_nop 0
	s_nop 0
	s_nop 0
	s_nop 0
	s_nop 0
	s_nop 0
	s_nop 0
	s_nop 0
	s_nop 0
	s_nop 0
	s_nop 0
	s_nop 0
	s_nop 0
	s_nop 0
	s_nop 0
	s_nop 0
	s_nop 0
	s_nop 0
	s_nop 0
	s_nop 0
	s_nop 0
	s_nop 0
	s_nop 0
	s_nop 0
	s_nop 0
	s_nop 0
	s_nop 0
	s_nop 0
	s_nop 0
	s_nop 0
	s_nop 0
	s_nop 0
	s_nop 0
	s_nop 0
	s_nop 0
	s_nop 0
	s_nop 0
	s_nop 0
	s_nop 0
	s_nop 0
	s_nop 0
	s_nop 0
	s_nop 0
	s_nop 0
	s_nop 0
	s_nop 0
	s_nop 0
	s_nop 0
	s_nop 0
	s_nop 0
	s_nop 0
	s_nop 0
	s_nop 0
	s_nop 0
	s_nop 0
	s_nop 0
	s_nop 0
	s_nop 0
	s_nop 0
	s_nop 0
	s_nop 0
	s_nop 0
	s_nop 0
	s_nop 0
	s_nop 0
	s_nop 0
	s_nop 0
	s_nop 0
	s_nop 0
	s_nop 0
	s_nop 0
	s_nop 0
	s_nop 0
	s_nop 0
	s_nop 0
	s_nop 0
	s_nop 0
	s_nop 0
	s_nop 0
	s_nop 0
	s_nop 0
	s_nop 0
	s_nop 0
	s_nop 0
	s_nop 0
	s_nop 0
	s_nop 0
	s_nop 0
	s_nop 0
	s_nop 0
	s_nop 0
	s_nop 0
	s_nop 0
	s_nop 0
	s_nop 0
	s_nop 0
	s_nop 0
	s_nop 0
	s_nop 0
	s_nop 0
	s_nop 0
	s_nop 0
	s_nop 0
	s_nop 0
	s_nop 0
	s_nop 0
	s_nop 0
	s_nop 0
	s_nop 0
	s_nop 0
	s_nop 0
	s_nop 0
	s_nop 0
	s_nop 0
	s_nop 0
	s_nop 0
	s_nop 0
	s_nop 0
	s_nop 0
	s_nop 0
	s_nop 0
	s_nop 0
	s_nop 0
	s_nop 0
	s_nop 0
	s_nop 0
	s_nop 0
	s_nop 0
	s_nop 0
	s_nop 0
	s_nop 0
	s_nop 0
	s_nop 0
	s_nop 0
	s_nop 0
	s_nop 0
	s_nop 0
	s_nop 0
	s_nop 0
	s_nop 0
	s_nop 0
	s_nop 0
	s_nop 0
	s_nop 0
	s_nop 0
	s_nop 0
	s_nop 0
	s_nop 0
	s_nop 0
	s_nop 0
	s_nop 0
	s_nop 0
	s_nop 0
	s_nop 0
	s_nop 0
	s_nop 0
	s_nop 0
	s_nop 0
	s_nop 0
	s_nop 0
	s_nop 0
	s_nop 0
	s_nop 0
	s_nop 0
	s_nop 0
	s_nop 0
	s_nop 0
	s_nop 0
	s_nop 0
	s_nop 0
	s_nop 0
	s_nop 0
	s_nop 0
	s_nop 0
	s_nop 0
	s_nop 0
	s_nop 0
	s_nop 0
	s_nop 0
	s_nop 0
	s_nop 0
	s_nop 0
	s_nop 0
	s_nop 0
	s_nop 0
	s_nop 0
	s_nop 0
	s_nop 0
	s_nop 0
	s_nop 0
	s_nop 0
	s_nop 0
	s_nop 0
	s_nop 0
	s_nop 0
	s_nop 0
	s_nop 0
	s_nop 0
	s_nop 0
	s_nop 0
	s_nop 0
	s_nop 0
	s_nop 0
	s_nop 0
	s_nop 0
	s_nop 0
	s_nop 0
	s_nop 0
	s_nop 0
	s_nop 0
	s_nop 0
	s_nop 0
	s_nop 0
	s_nop 0
	s_nop 0
	s_nop 0
	s_nop 0
	s_nop 0
	s_nop 0
	s_nop 0
	s_nop 0
	s_nop 0
	s_nop 0
	s_nop 0
	s_nop 0
	s_nop 0
	s_nop 0
	s_nop 0
	s_nop 0
	s_nop 0
	s_nop 0
	s_nop 0
	s_nop 0
	s_nop 0
	s_nop 0
	s_nop 0
	s_nop 0
	s_nop 0
	s_nop 0
	s_nop 0
	s_nop 0
	s_nop 0
	s_nop 0
	s_nop 0
	s_nop 0
	s_nop 0
	s_nop 0
	s_nop 0
	s_nop 0
	s_nop 0
	s_nop 0
	s_nop 0
	s_nop 0
	s_nop 0
	s_nop 0
	s_nop 0
	s_nop 0
	s_nop 0
	s_nop 0
	s_nop 0
	s_nop 0
	s_nop 0
	s_nop 0
	s_nop 0
	s_nop 0
	s_nop 0
	s_nop 0
	s_nop 0
	s_nop 0
	s_nop 0
	s_nop 0
	s_nop 0
	s_nop 0
	s_nop 0
	s_nop 0
	s_nop 0
	s_nop 0
	s_nop 0
	s_nop 0
	s_nop 0
	s_nop 0
	s_nop 0
	s_nop 0
	s_nop 0
	s_nop 0
	s_nop 0
	s_nop 0
	s_nop 0
	s_nop 0
	s_nop 0
	s_nop 0
	s_nop 0
	s_nop 0
	s_nop 0
	s_nop 0
	s_nop 0
	s_nop 0
	s_nop 0
	s_nop 0
	s_nop 0
	s_nop 0
	s_nop 0
	s_nop 0
	s_nop 0
	s_nop 0
	s_nop 0
	s_nop 0
	s_nop 0
	s_nop 0
	s_nop 0
	s_nop 0
	s_nop 0
	s_nop 0
	s_nop 0
	s_nop 0
	s_nop 0
	s_nop 0
	s_nop 0
	s_nop 0
	s_nop 0
	s_nop 0
	s_nop 0
	s_nop 0
	s_nop 0
	s_nop 0
	s_nop 0
	s_nop 0
	s_nop 0
	s_nop 0
	s_nop 0
	s_nop 0
	s_nop 0
	s_nop 0
	s_nop 0
	s_nop 0
	s_nop 0
	s_nop 0
	s_nop 0
	s_nop 0
	s_nop 0
	s_nop 0
	s_nop 0
	s_nop 0
	s_nop 0
	s_nop 0
	s_nop 0
	s_nop 0
	s_nop 0
	s_nop 0
	s_nop 0
	s_nop 0
	s_nop 0
	s_nop 0
	s_nop 0
	s_nop 0
	s_nop 0
	s_nop 0
	s_nop 0
	s_nop 0
	s_nop 0
	s_nop 0
	s_nop 0
	s_nop 0
	s_nop 0
	s_nop 0
	s_nop 0
	s_nop 0
	s_nop 0
	s_nop 0
	s_nop 0
	s_nop 0
	s_nop 0
	s_nop 0
	s_nop 0
	s_nop 0
	s_nop 0
	s_nop 0
